# stack1 + C_MERGE fragment loads issued with the lse loads + B_MIX weight-block staging loads batched
# speedup vs baseline: 1.0168x; 1.0099x over previous
.LBB0_121:
	v_ashrrev_i32_e32 v4, 7, v2
	v_ashrrev_i32_e32 v5, 31, v4
	s_mov_b64 s[10:11], 0x4000
	v_lshl_add_u64 v[8:9], v[4:5], 0, s[10:11]
	v_lshlrev_b64 v[6:7], 6, v[4:5]
	v_lshrrev_b32_e32 v0, 4, v3
	v_lshlrev_b64 v[10:11], 6, v[8:9]
	v_lshl_add_u64 v[6:7], s[16:17], 0, v[6:7]
	v_and_b32_e32 v0, 60, v0
	v_lshl_add_u64 v[10:11], s[16:17], 0, v[10:11]
	v_lshl_add_u64 v[6:7], v[6:7], 0, v[0:1]
	v_lshl_add_u64 v[10:11], v[10:11], 0, v[0:1]
	s_mov_b32 s7, 0x200000
	global_load_dword v12, v[6:7], off
	global_load_dword v0, v[10:11], off
	v_add_co_u32_e32 v6, vcc, s7, v6
	v_and_b32_e32 v14, 0x3f8, v3
	s_nop 0
	v_addc_co_u32_e32 v7, vcc, 0, v7, vcc
	global_load_dword v10, v[6:7], off
	v_lshlrev_b64 v[4:5], 11, v[4:5]
	v_add_u32_e32 v2, s18, v2
	v_add_u32_e32 v3, s19, v3
	v_lshlrev_b32_e32 v58, 1, v14
	v_mov_b32_e32 v59, 0
	v_lshl_add_u64 v[52:53], s[2:3], 0, v[4:5]
	v_lshl_add_u64 v[54:55], s[14:15], 0, v[4:5]
	v_lshlrev_b64 v[56:57], 11, v[8:9]
	v_lshl_add_u64 v[52:53], v[52:53], 0, v[58:59]
	v_lshl_add_u64 v[54:55], v[54:55], 0, v[58:59]
	v_lshl_add_u64 v[56:57], s[14:15], 0, v[56:57]
	v_lshl_add_u64 v[56:57], v[56:57], 0, v[58:59]
	global_load_dwordx4 v[40:43], v[52:53], off
	global_load_dwordx4 v[44:47], v[54:55], off
	global_load_dwordx4 v[48:51], v[56:57], off
	s_waitcnt vmcnt(3)
	v_max3_f32 v11, v12, v0, v10
	v_sub_f32_e32 v6, v12, v11
	v_sub_f32_e32 v0, v0, v11
	v_mul_f32_e32 v6, 0x3fb8aa3b, v6
	v_mul_f32_e32 v0, 0x3fb8aa3b, v0
	v_exp_f32_e32 v7, v6
	v_exp_f32_e32 v6, v0
	v_sub_f32_e32 v0, v10, v11
	v_mul_f32_e32 v0, 0x3fb8aa3b, v0
	v_exp_f32_e32 v0, v0
	v_add_f32_e32 v10, v7, v6
	v_add_f32_e32 v10, v0, v10
	v_div_scale_f32 v11, s[10:11], v10, v10, 1.0
	v_rcp_f32_e32 v12, v11
	s_nop 0
	v_fma_f32 v13, -v11, v12, 1.0
	v_fmac_f32_e32 v12, v13, v12
	v_div_scale_f32 v13, vcc, 1.0, v10, 1.0
	v_mul_f32_e32 v15, v13, v12
	v_fma_f32 v16, -v11, v15, v13
	v_fmac_f32_e32 v15, v16, v12
	v_fma_f32 v11, -v11, v15, v13
	v_div_fmas_f32 v11, v11, v12, v15
	v_div_fixup_f32 v10, v11, v10, 1.0
	v_mul_f32_e32 v16, v0, v10
	v_lshl_add_u64 v[12:13], s[2:3], 0, v[4:5]
	v_lshlrev_b32_e32 v0, 1, v14
	v_lshl_add_u64 v[4:5], s[14:15], 0, v[4:5]
	v_lshl_add_u64 v[18:19], v[12:13], 0, v[0:1]
	v_lshl_add_u64 v[12:13], v[4:5], 0, v[0:1]
	v_lshlrev_b64 v[4:5], 11, v[8:9]
	v_lshl_add_u64 v[4:5], s[14:15], 0, v[4:5]
	v_lshl_add_u64 v[14:15], v[4:5], 0, v[0:1]
	v_pk_mul_f32 v[20:21], v[6:7], v[10:11] op_sel_hi:[1,0]
	v_cmp_le_i32_e32 vcc, s13, v2
	s_or_b64 s[4:5], vcc, s[4:5]
	s_waitcnt vmcnt(2)
	v_mov_b64_e32 v[4:5], v[40:41]
	v_mov_b64_e32 v[6:7], v[42:43]
	v_lshlrev_b32_e32 v24, 16, v4
	s_waitcnt vmcnt(1)
	v_mov_b64_e32 v[8:9], v[44:45]
	v_mov_b64_e32 v[10:11], v[46:47]
	v_lshlrev_b32_e32 v25, 16, v9
	v_lshlrev_b32_e32 v23, 16, v5
	v_lshlrev_b32_e32 v22, 16, v8
	v_pk_mul_f32 v[24:25], v[20:21], v[24:25] op_sel:[1,0] op_sel_hi:[0,1]
	v_pk_fma_f32 v[22:23], v[20:21], v[22:23], v[24:25]
	s_waitcnt vmcnt(0)
	v_mov_b64_e32 v[12:13], v[48:49]
	v_mov_b64_e32 v[14:15], v[50:51]
	v_lshlrev_b32_e32 v25, 16, v13
	v_lshlrev_b32_e32 v24, 16, v12
	v_pk_fma_f32 v[22:23], v[16:17], v[24:25], v[22:23] op_sel_hi:[0,1,1]
	v_and_b32_e32 v25, 0xffff0000, v5
	v_and_b32_e32 v5, 0xffff0000, v9
	v_and_b32_e32 v4, 0xffff0000, v4
	v_and_b32_e32 v24, 0xffff0000, v8
	v_pk_mul_f32 v[4:5], v[20:21], v[4:5] op_sel:[1,0] op_sel_hi:[0,1]
	v_pk_fma_f32 v[4:5], v[20:21], v[24:25], v[4:5]
	v_and_b32_e32 v9, 0xffff0000, v13
	v_and_b32_e32 v8, 0xffff0000, v12
	v_pk_fma_f32 v[4:5], v[16:17], v[8:9], v[4:5] op_sel_hi:[0,1,1]
	v_and_b32_sdwa v12, v4, v152 dst_sel:DWORD dst_unused:UNUSED_PAD src0_sel:WORD_1 src1_sel:DWORD
	v_and_b32_sdwa v8, v22, v152 dst_sel:DWORD dst_unused:UNUSED_PAD src0_sel:WORD_1 src1_sel:DWORD
	v_add3_u32 v4, v4, v12, s87
	v_add3_u32 v8, v22, v8, s87
	v_and_b32_sdwa v9, v5, v152 dst_sel:DWORD dst_unused:UNUSED_PAD src0_sel:WORD_1 src1_sel:DWORD
	v_and_b32_e32 v4, 0xffff0000, v4
	v_lshlrev_b32_e32 v13, 16, v11
	v_lshlrev_b32_e32 v12, 16, v6
	v_and_b32_sdwa v0, v23, v152 dst_sel:DWORD dst_unused:UNUSED_PAD src0_sel:WORD_1 src1_sel:DWORD
	v_add3_u32 v5, v5, v9, s87
	v_or_b32_sdwa v4, v4, v8 dst_sel:DWORD dst_unused:UNUSED_PAD src0_sel:DWORD src1_sel:WORD_1
	v_lshlrev_b32_e32 v9, 16, v7
	v_lshlrev_b32_e32 v8, 16, v10
	v_and_b32_e32 v25, 0xffff0000, v7
	v_and_b32_e32 v7, 0xffff0000, v11
	v_and_b32_e32 v6, 0xffff0000, v6
	v_pk_mul_f32 v[12:13], v[20:21], v[12:13] op_sel:[1,0] op_sel_hi:[0,1]
	v_add3_u32 v0, v23, v0, s87
	v_lshlrev_b32_e32 v23, 16, v15
	v_lshlrev_b32_e32 v22, 16, v14
	v_and_b32_e32 v24, 0xffff0000, v10
	v_pk_fma_f32 v[8:9], v[20:21], v[8:9], v[12:13]
	v_pk_mul_f32 v[6:7], v[20:21], v[6:7] op_sel:[1,0] op_sel_hi:[0,1]
	v_and_b32_e32 v5, 0xffff0000, v5
	v_and_b32_e32 v11, 0xffff0000, v15
	v_and_b32_e32 v10, 0xffff0000, v14
	v_pk_fma_f32 v[8:9], v[16:17], v[22:23], v[8:9] op_sel_hi:[0,1,1]
	v_pk_fma_f32 v[6:7], v[20:21], v[24:25], v[6:7]
	v_or_b32_sdwa v5, v5, v0 dst_sel:DWORD dst_unused:UNUSED_PAD src0_sel:DWORD src1_sel:WORD_1
	v_pk_fma_f32 v[6:7], v[16:17], v[10:11], v[6:7] op_sel_hi:[0,1,1]
	v_and_b32_sdwa v0, v9, v152 dst_sel:DWORD dst_unused:UNUSED_PAD src0_sel:WORD_1 src1_sel:DWORD
	v_and_b32_sdwa v10, v8, v152 dst_sel:DWORD dst_unused:UNUSED_PAD src0_sel:WORD_1 src1_sel:DWORD
	v_add3_u32 v8, v8, v10, s87
	v_add3_u32 v0, v9, v0, s87
	v_and_b32_sdwa v9, v7, v152 dst_sel:DWORD dst_unused:UNUSED_PAD src0_sel:WORD_1 src1_sel:DWORD
	v_and_b32_sdwa v10, v6, v152 dst_sel:DWORD dst_unused:UNUSED_PAD src0_sel:WORD_1 src1_sel:DWORD
	v_add3_u32 v7, v7, v9, s87
	v_add3_u32 v6, v6, v10, s87
	v_and_b32_e32 v7, 0xffff0000, v7
	v_and_b32_e32 v6, 0xffff0000, v6
	v_or_b32_sdwa v7, v7, v0 dst_sel:DWORD dst_unused:UNUSED_PAD src0_sel:DWORD src1_sel:WORD_1
	v_or_b32_sdwa v6, v6, v8 dst_sel:DWORD dst_unused:UNUSED_PAD src0_sel:DWORD src1_sel:WORD_1
	global_store_dwordx4 v[18:19], v[4:7], off
	s_andn2_b64 exec, exec, s[4:5]
	s_cbranch_execnz .LBB0_121

.LBB0_148:
	v_mov_b32_e32 v181, 0
	v_ashrrev_i32_e32 v184, 4, v3
	v_add_u32_e32 v186, s15, v184
	v_ashrrev_i32_e32 v187, 31, v186
	v_lshlrev_b32_e32 v180, 1, v2
	v_lshlrev_b64 v[186:187], 8, v[186:187]
	v_and_b32_e32 v180, 0xf0, v180
	v_lshl_add_u64 v[186:187], s[98:99], 0, v[186:187]
	v_lshl_add_u64 v[186:187], v[186:187], 0, v[180:181]
	global_load_dwordx4 v[160:163], v[186:187], off
	s_movk_i32 s16, 0x110
	v_mul_lo_u32 v184, v184, s16
	v_add3_u32 v176, s23, v184, v180
	v_add_u32_e32 v182, 0x200, v3
	v_add_u32_e32 v183, 0x1000, v2
	v_ashrrev_i32_e32 v184, 4, v182
	v_add_u32_e32 v186, s15, v184
	v_ashrrev_i32_e32 v187, 31, v186
	v_lshlrev_b32_e32 v180, 1, v183
	v_lshlrev_b64 v[186:187], 8, v[186:187]
	v_and_b32_e32 v180, 0xf0, v180
	v_lshl_add_u64 v[186:187], s[98:99], 0, v[186:187]
	v_lshl_add_u64 v[186:187], v[186:187], 0, v[180:181]
	global_load_dwordx4 v[164:167], v[186:187], off
	v_mul_lo_u32 v184, v184, s16
	v_add3_u32 v177, s23, v184, v180
	v_add_u32_e32 v182, 0x400, v3
	v_add_u32_e32 v183, 0x2000, v2
	v_ashrrev_i32_e32 v184, 4, v182
	v_add_u32_e32 v186, s15, v184
	v_ashrrev_i32_e32 v187, 31, v186
	v_lshlrev_b32_e32 v180, 1, v183
	v_lshlrev_b64 v[186:187], 8, v[186:187]
	v_and_b32_e32 v180, 0xf0, v180
	v_lshl_add_u64 v[186:187], s[98:99], 0, v[186:187]
	v_lshl_add_u64 v[186:187], v[186:187], 0, v[180:181]
	global_load_dwordx4 v[168:171], v[186:187], off
	v_mul_lo_u32 v184, v184, s16
	v_add3_u32 v178, s23, v184, v180
	v_add_u32_e32 v182, 0x600, v3
	v_add_u32_e32 v183, 0x3000, v2
	v_ashrrev_i32_e32 v184, 4, v182
	v_add_u32_e32 v186, s15, v184
	v_ashrrev_i32_e32 v187, 31, v186
	v_lshlrev_b32_e32 v180, 1, v183
	v_lshlrev_b64 v[186:187], 8, v[186:187]
	v_and_b32_e32 v180, 0xf0, v180
	v_lshl_add_u64 v[186:187], s[98:99], 0, v[186:187]
	v_lshl_add_u64 v[186:187], v[186:187], 0, v[180:181]
	global_load_dwordx4 v[172:175], v[186:187], off
	v_mul_lo_u32 v184, v184, s16
	v_add3_u32 v179, s23, v184, v180
	s_waitcnt vmcnt(0)
	ds_write_b128 v176, v[160:163]
	ds_write_b128 v177, v[164:167]
	ds_write_b128 v178, v[168:171]
	ds_write_b128 v179, v[172:175]
